# c14_noprio
# baseline (speedup 1.0000x reference)
.LBB0_862:
	s_and_b64 s[54:55], s[56:57], exec
	s_cselect_b32 s8, s33, s62
	s_or_b32 s67, s36, s8
	s_mul_hi_u32 s55, s67, 0xc00
	s_mul_i32 s58, s37, 0xc00
	s_mul_i32 s54, s67, 0xc00
	s_add_i32 s55, s55, s58
	v_mov_b32_e32 v2, v230
	s_add_u32 s60, s63, s54
	s_addc_u32 s61, s64, s55
	v_readfirstlane_b32 s58, v2
	s_ashr_i32 s55, s58, 6
	v_and_b32_e32 v36, 31, v2
	s_lshl_b32 s54, s55, 5
	v_bfe_u32 v37, v2, 5, 1
	v_or_b32_e32 v0, s54, v36
	v_mov_b64_e32 v[4:5], s[60:61]
	v_mad_i64_i32 v[4:5], s[60:61], v0, s27, v[4:5]
	v_lshlrev_b32_e32 v0, 4, v37
	v_lshl_add_u64 v[4:5], v[4:5], 0, v[0:1]
	global_load_dwordx4 v[188:191], v[4:5], off nt
	global_load_dwordx4 v[184:187], v[4:5], off offset:32 nt
	global_load_dwordx4 v[180:183], v[4:5], off offset:64 nt
	global_load_dwordx4 v[176:179], v[4:5], off offset:96 nt
	global_load_dwordx4 v[172:175], v[4:5], off offset:128 nt
	global_load_dwordx4 v[168:171], v[4:5], off offset:160 nt
	global_load_dwordx4 v[164:167], v[4:5], off offset:192 nt
	global_load_dwordx4 v[160:163], v[4:5], off offset:224 nt
	global_load_dwordx4 v[156:159], v[4:5], off offset:256 nt
	global_load_dwordx4 v[152:155], v[4:5], off offset:288 nt
	global_load_dwordx4 v[148:151], v[4:5], off offset:320 nt
	global_load_dwordx4 v[144:147], v[4:5], off offset:352 nt
	s_cmp_lt_i32 s55, 4
	s_cbranch_scc1 .LBB0_864
	s_setprio 0

.LBB0_1406:
	s_lshl_b32 s18, s27, 7
	v_mov_b32_e32 v4, v205
	s_add_u32 s44, s61, s18
	s_addc_u32 s45, s83, 0
	v_readfirstlane_b32 s18, v4
	s_ashr_i32 s22, s18, 6
	v_and_b32_e32 v38, 31, v4
	s_lshl_b32 s19, s22, 5
	v_bfe_u32 v40, v4, 5, 1
	v_or_b32_e32 v2, s19, v38
	v_mov_b64_e32 v[0:1], s[44:45]
	s_movk_i32 s31, 0x1800
	v_mad_i64_i32 v[0:1], s[44:45], v2, s31, v[0:1]
	v_lshlrev_b32_e32 v2, 4, v40
	v_lshl_add_u64 v[0:1], v[0:1], 0, v[2:3]
	global_load_dwordx4 v[156:159], v[0:1], off nt
	global_load_dwordx4 v[152:155], v[0:1], off offset:32 nt
	global_load_dwordx4 v[148:151], v[0:1], off offset:64 nt
	global_load_dwordx4 v[144:147], v[0:1], off offset:96 nt
	v_cvt_pk_bf16_f32 v0, v210, v3
	s_cmp_lt_i32 s22, 4
	v_lshlrev_b32_e32 v0, 16, v0
	v_sub_f32_e32 v1, v210, v0
	v_cvt_pk_bf16_f32 v160, v0, v1
	s_cbranch_scc1 .LBB0_1408
	s_setprio 0
